# natten mask: batched bias loads + VALU window test instead of 32 serialized exec-masked LDS reads
# baseline (speedup 1.0000x reference)
.LBB0_550:
	s_cmp_gt_u32 s89, 3
	s_cselect_b64 s[96:97], -1, 0
	s_cmp_lt_u32 s89, 4
	s_cbranch_scc1 .LBB0_616
	s_add_i32 s0, s7, s89
	s_add_i32 s8, s0, -4
	s_cmp_ge_i32 s8, s91
	v_readlane_b32 s9, v253, 10
	s_cselect_b64 s[0:1], -1, 0
	s_cmp_lt_i32 s8, s9
	s_cselect_b64 s[8:9], -1, 0
	s_and_b64 s[68:69], s[0:1], s[8:9]
	v_readlane_b32 s0, v253, 6
	s_add_i32 s0, s0, s88
	s_sub_i32 s8, s0, 31
	s_and_b64 s[0:1], s[68:69], exec
	s_cselect_b32 s0, s8, 0
	v_lshl_add_u32 v82, s0, 2, v150
	v_readlane_b32 s0, v253, 24
	v_readlane_b32 s1, v253, 25
	s_and_b64 s[8:9], s[68:69], s[0:1]
	v_mov_b32_e32 v0, 0
	v_lshl_add_u32 v83, v151, 2, v82
	v_mov_b32_e32 v82, 0
	s_and_b64 vcc, exec, s[68:69]
	s_cbranch_vccz .Lnme_out
	v_sub_u32_e32 v104, 0, v150
	v_sub_u32_e64 v104, v104, 32 clamp
	v_min_u32_e32 v104, 0xc0, v104
	v_lshlrev_b32_e32 v105, 2, v151
	v_sub_u32_e32 v104, v105, v104
	ds_read_b32 v84, v83 offset:32828
	ds_read_b32 v85, v83 offset:32832
	ds_read_b32 v86, v83 offset:32836
	ds_read_b32 v87, v83 offset:32840
	ds_read_b32 v88, v83 offset:32844
	ds_read_b32 v89, v83 offset:32848
	ds_read_b32 v90, v83 offset:32852
	ds_read_b32 v91, v83 offset:32856
	ds_read_b32 v92, v83 offset:32892
	ds_read_b32 v93, v83 offset:32896
	ds_read_b32 v94, v83 offset:32900
	ds_read_b32 v95, v83 offset:32904
	ds_read_b32 v96, v83 offset:32908
	ds_read_b32 v97, v83 offset:32912
	ds_read_b32 v98, v83 offset:32916
	ds_read_b32 v99, v83 offset:32920
	s_waitcnt lgkmcnt(8)
	v_add_u32_e32 v100, 0, v104
	v_add_u32_e32 v101, 4, v104
	v_add_u32_e32 v102, 8, v104
	v_add_u32_e32 v103, 12, v104
	v_fmac_f32_e32 v50, 0x3fb8aa3b, v84
	v_fmac_f32_e32 v51, 0x3fb8aa3b, v85
	v_fmac_f32_e32 v52, 0x3fb8aa3b, v86
	v_fmac_f32_e32 v53, 0x3fb8aa3b, v87
	v_cmp_gt_u32_e32 vcc, 64, v100
	v_cmp_gt_u32_e64 s[0:1], 64, v101
	v_cmp_gt_u32_e64 s[8:9], 64, v102
	v_cmp_gt_u32_e64 s[10:11], 64, v103
	v_cndmask_b32_e32 v50, v205, v50, vcc
	v_cndmask_b32_e64 v51, v205, v51, s[0:1]
	v_cndmask_b32_e64 v52, v205, v52, s[8:9]
	v_cndmask_b32_e64 v53, v205, v53, s[10:11]
	v_add_u32_e32 v100, 16, v104
	v_add_u32_e32 v101, 20, v104
	v_add_u32_e32 v102, 24, v104
	v_add_u32_e32 v103, 28, v104
	v_fmac_f32_e32 v54, 0x3fb8aa3b, v88
	v_fmac_f32_e32 v55, 0x3fb8aa3b, v89
	v_fmac_f32_e32 v56, 0x3fb8aa3b, v90
	v_fmac_f32_e32 v57, 0x3fb8aa3b, v91
	v_cmp_gt_u32_e32 vcc, 64, v100
	v_cmp_gt_u32_e64 s[0:1], 64, v101
	v_cmp_gt_u32_e64 s[8:9], 64, v102
	v_cmp_gt_u32_e64 s[10:11], 64, v103
	v_cndmask_b32_e32 v54, v205, v54, vcc
	v_cndmask_b32_e64 v55, v205, v55, s[0:1]
	v_cndmask_b32_e64 v56, v205, v56, s[8:9]
	v_cndmask_b32_e64 v57, v205, v57, s[10:11]
	ds_read_b32 v84, v83 offset:32956
	ds_read_b32 v85, v83 offset:32960
	ds_read_b32 v86, v83 offset:32964
	ds_read_b32 v87, v83 offset:32968
	ds_read_b32 v88, v83 offset:32972
	ds_read_b32 v89, v83 offset:32976
	ds_read_b32 v90, v83 offset:32980
	ds_read_b32 v91, v83 offset:32984
	s_waitcnt lgkmcnt(8)
	v_add_u32_e32 v100, 64, v104
	v_add_u32_e32 v101, 68, v104
	v_add_u32_e32 v102, 72, v104
	v_add_u32_e32 v103, 76, v104
	v_fmac_f32_e32 v58, 0x3fb8aa3b, v92
	v_fmac_f32_e32 v59, 0x3fb8aa3b, v93
	v_fmac_f32_e32 v60, 0x3fb8aa3b, v94
	v_fmac_f32_e32 v61, 0x3fb8aa3b, v95
	v_cmp_gt_u32_e32 vcc, 64, v100
	v_cmp_gt_u32_e64 s[0:1], 64, v101
	v_cmp_gt_u32_e64 s[8:9], 64, v102
	v_cmp_gt_u32_e64 s[10:11], 64, v103
	v_cndmask_b32_e32 v58, v205, v58, vcc
	v_cndmask_b32_e64 v59, v205, v59, s[0:1]
	v_cndmask_b32_e64 v60, v205, v60, s[8:9]
	v_cndmask_b32_e64 v61, v205, v61, s[10:11]
	v_add_u32_e32 v100, 80, v104
	v_add_u32_e32 v101, 84, v104
	v_add_u32_e32 v102, 88, v104
	v_add_u32_e32 v103, 92, v104
	v_fmac_f32_e32 v62, 0x3fb8aa3b, v96
	v_fmac_f32_e32 v63, 0x3fb8aa3b, v97
	v_fmac_f32_e32 v64, 0x3fb8aa3b, v98
	v_fmac_f32_e32 v65, 0x3fb8aa3b, v99
	v_cmp_gt_u32_e32 vcc, 64, v100
	v_cmp_gt_u32_e64 s[0:1], 64, v101
	v_cmp_gt_u32_e64 s[8:9], 64, v102
	v_cmp_gt_u32_e64 s[10:11], 64, v103
	v_cndmask_b32_e32 v62, v205, v62, vcc
	v_cndmask_b32_e64 v63, v205, v63, s[0:1]
	v_cndmask_b32_e64 v64, v205, v64, s[8:9]
	v_cndmask_b32_e64 v65, v205, v65, s[10:11]
	ds_read_b32 v92, v83 offset:33020
	ds_read_b32 v93, v83 offset:33024
	ds_read_b32 v94, v83 offset:33028
	ds_read_b32 v95, v83 offset:33032
	ds_read_b32 v96, v83 offset:33036
	ds_read_b32 v97, v83 offset:33040
	ds_read_b32 v98, v83 offset:33044
	ds_read_b32 v99, v83 offset:33048
	s_waitcnt lgkmcnt(8)
	v_add_u32_e32 v100, 128, v104
	v_add_u32_e32 v101, 132, v104
	v_add_u32_e32 v102, 136, v104
	v_add_u32_e32 v103, 140, v104
	v_fmac_f32_e32 v66, 0x3fb8aa3b, v84
	v_fmac_f32_e32 v67, 0x3fb8aa3b, v85
	v_fmac_f32_e32 v68, 0x3fb8aa3b, v86
	v_fmac_f32_e32 v69, 0x3fb8aa3b, v87
	v_cmp_gt_u32_e32 vcc, 64, v100
	v_cmp_gt_u32_e64 s[0:1], 64, v101
	v_cmp_gt_u32_e64 s[8:9], 64, v102
	v_cmp_gt_u32_e64 s[10:11], 64, v103
	v_cndmask_b32_e32 v66, v205, v66, vcc
	v_cndmask_b32_e64 v67, v205, v67, s[0:1]
	v_cndmask_b32_e64 v68, v205, v68, s[8:9]
	v_cndmask_b32_e64 v69, v205, v69, s[10:11]
	v_add_u32_e32 v100, 144, v104
	v_add_u32_e32 v101, 148, v104
	v_add_u32_e32 v102, 152, v104
	v_add_u32_e32 v103, 156, v104
	v_fmac_f32_e32 v70, 0x3fb8aa3b, v88
	v_fmac_f32_e32 v71, 0x3fb8aa3b, v89
	v_fmac_f32_e32 v72, 0x3fb8aa3b, v90
	v_fmac_f32_e32 v73, 0x3fb8aa3b, v91
	v_cmp_gt_u32_e32 vcc, 64, v100
	v_cmp_gt_u32_e64 s[0:1], 64, v101
	v_cmp_gt_u32_e64 s[8:9], 64, v102
	v_cmp_gt_u32_e64 s[10:11], 64, v103
	v_cndmask_b32_e32 v70, v205, v70, vcc
	v_cndmask_b32_e64 v71, v205, v71, s[0:1]
	v_cndmask_b32_e64 v72, v205, v72, s[8:9]
	v_cndmask_b32_e64 v73, v205, v73, s[10:11]
	s_waitcnt lgkmcnt(0)
	v_add_u32_e32 v100, 192, v104
	v_add_u32_e32 v101, 196, v104
	v_add_u32_e32 v102, 200, v104
	v_add_u32_e32 v103, 204, v104
	v_fmac_f32_e32 v74, 0x3fb8aa3b, v92
	v_fmac_f32_e32 v75, 0x3fb8aa3b, v93
	v_fmac_f32_e32 v76, 0x3fb8aa3b, v94
	v_fmac_f32_e32 v77, 0x3fb8aa3b, v95
	v_cmp_gt_u32_e32 vcc, 64, v100
	v_cmp_gt_u32_e64 s[0:1], 64, v101
	v_cmp_gt_u32_e64 s[8:9], 64, v102
	v_cmp_gt_u32_e64 s[10:11], 64, v103
	v_cndmask_b32_e32 v74, v205, v74, vcc
	v_cndmask_b32_e64 v75, v205, v75, s[0:1]
	v_cndmask_b32_e64 v76, v205, v76, s[8:9]
	v_cndmask_b32_e64 v77, v205, v77, s[10:11]
	v_add_u32_e32 v100, 208, v104
	v_add_u32_e32 v101, 212, v104
	v_add_u32_e32 v102, 216, v104
	v_add_u32_e32 v103, 220, v104
	v_fmac_f32_e32 v78, 0x3fb8aa3b, v96
	v_fmac_f32_e32 v79, 0x3fb8aa3b, v97
	v_fmac_f32_e32 v80, 0x3fb8aa3b, v98
	v_fmac_f32_e32 v81, 0x3fb8aa3b, v99
	v_cmp_gt_u32_e32 vcc, 64, v100
	v_cmp_gt_u32_e64 s[0:1], 64, v101
	v_cmp_gt_u32_e64 s[8:9], 64, v102
	v_cmp_gt_u32_e64 s[10:11], 64, v103
	v_cndmask_b32_e32 v78, v205, v78, vcc
	v_cndmask_b32_e64 v79, v205, v79, s[0:1]
	v_cndmask_b32_e64 v80, v205, v80, s[8:9]
	v_cndmask_b32_e64 v81, v205, v81, s[10:11]
	s_branch .Lnme_done
.Lnme_out:
	v_mov_b32_e32 v50, v205
	v_mov_b32_e32 v51, v205
	v_mov_b32_e32 v52, v205
	v_mov_b32_e32 v53, v205
	v_mov_b32_e32 v54, v205
	v_mov_b32_e32 v55, v205
	v_mov_b32_e32 v56, v205
	v_mov_b32_e32 v57, v205
	v_mov_b32_e32 v58, v205
	v_mov_b32_e32 v59, v205
	v_mov_b32_e32 v60, v205
	v_mov_b32_e32 v61, v205
	v_mov_b32_e32 v62, v205
	v_mov_b32_e32 v63, v205
	v_mov_b32_e32 v64, v205
	v_mov_b32_e32 v65, v205
	v_mov_b32_e32 v66, v205
	v_mov_b32_e32 v67, v205
	v_mov_b32_e32 v68, v205
	v_mov_b32_e32 v69, v205
	v_mov_b32_e32 v70, v205
	v_mov_b32_e32 v71, v205
	v_mov_b32_e32 v72, v205
	v_mov_b32_e32 v73, v205
	v_mov_b32_e32 v74, v205
	v_mov_b32_e32 v75, v205
	v_mov_b32_e32 v76, v205
	v_mov_b32_e32 v77, v205
	v_mov_b32_e32 v78, v205
	v_mov_b32_e32 v79, v205
	v_mov_b32_e32 v80, v205
	v_mov_b32_e32 v81, v205
.Lnme_done:
.LBB0_616:
	ds_read_b128 v[82:85], v156 offset:8192
	ds_read_b128 v[166:169], v156 offset:12288
	v_exp_f32_e32 v0, v50
	v_exp_f32_e32 v86, v51
	v_exp_f32_e32 v87, v58
	ds_read_b128 v[174:177], v157 offset:8192
	ds_read_b128 v[178:181], v157 offset:12288
	v_exp_f32_e32 v132, v53
	v_exp_f32_e32 v133, v60
	s_waitcnt lgkmcnt(0)
	v_mfma_f32_32x32x16_bf16 v[98:113], v[82:85], v[114:117], v[34:49]
	v_exp_f32_e32 v82, v59
	v_add_f32_e32 v83, 0, v0
	v_cvt_pk_bf16_f32 v130, v0, v86
	v_exp_f32_e32 v0, v52
	v_add_f32_e32 v83, v86, v83
	v_add_f32_e32 v83, v87, v83
	v_add_f32_e32 v131, v82, v83
	v_exp_f32_e32 v135, v61
	v_cvt_pk_bf16_f32 v134, v87, v82
	v_mfma_f32_32x32x16_bf16 v[82:97], v[166:169], v[114:117], v[34:49]
	v_add_f32_e32 v131, v0, v131
	v_add_f32_e32 v131, v132, v131
	v_add_f32_e32 v131, v133, v131
	v_add_f32_e32 v136, v135, v131
	v_cvt_pk_bf16_f32 v131, v0, v132
	v_exp_f32_e32 v0, v54
	v_cvt_pk_bf16_f32 v135, v133, v135
	ds_read_b128 v[166:169], v160 offset:8192
	v_exp_f32_e32 v132, v55
	ds_read_b128 v[182:185], v160 offset:12288
	v_exp_f32_e32 v133, v62
	v_mfma_f32_32x32x16_bf16 v[98:113], v[174:177], v[118:121], v[98:113]
	v_exp_f32_e32 v137, v63
	v_add_f32_e32 v136, v0, v136
	v_add_f32_e32 v136, v132, v136
	v_add_f32_e32 v136, v133, v136
	v_cvt_pk_bf16_f32 v132, v0, v132
	v_exp_f32_e32 v0, v56
	v_add_f32_e32 v146, v137, v136
	v_cvt_pk_bf16_f32 v136, v133, v137
	v_exp_f32_e32 v133, v57
	v_exp_f32_e32 v137, v64
	v_exp_f32_e32 v148, v65
	s_waitcnt lgkmcnt(0)
	v_mfma_f32_32x32x16_bf16 v[98:113], v[166:169], v[122:125], v[98:113]
	v_add_f32_e32 v146, v0, v146
	v_add_f32_e32 v146, v133, v146
	v_add_f32_e32 v146, v137, v146
	v_cvt_pk_bf16_f32 v133, v0, v133
	v_cvt_pk_bf16_f32 v137, v137, v148
	ds_read_b128 v[166:169], v161 offset:8192
	ds_read_b128 v[174:177], v161 offset:12288
	s_waitcnt lgkmcnt(0)
	v_mfma_f32_32x32x16_bf16 v[98:113], v[166:169], v[126:129], v[98:113]
	v_add_f32_e32 v149, v148, v146
	v_mfma_f32_32x32x16_bf16 v[82:97], v[178:181], v[118:121], v[82:97]
	v_mfma_f32_32x32x16_bf16 v[82:97], v[182:185], v[122:125], v[82:97]
	v_mfma_f32_32x32x16_bf16 v[82:97], v[174:177], v[126:129], v[82:97]
	s_cmp_eq_u32 s89, 0
	s_cselect_b64 s[0:1], -1, 0
	s_cmp_lg_u32 s89, 0
	v_cmp_ngt_f32_e32 vcc, s72, v149
	s_cselect_b64 s[8:9], -1, 0
	s_or_b64 vcc, s[0:1], vcc
	s_cbranch_vccz .LBB0_620
	v_max_f32_e32 v0, v53, v53
	v_max_f32_e32 v130, v52, v52
	v_max_f32_e32 v0, v130, v0
	v_max_f32_e32 v130, v55, v55
	v_max_f32_e32 v131, v54, v54
	v_max_f32_e32 v130, v131, v130
	v_max_f32_e32 v131, v57, v57
	v_max_f32_e32 v132, v56, v56
	v_max3_f32 v0, v50, v51, v0
	v_max_f32_e32 v131, v132, v131
	v_max3_f32 v0, v0, v130, v131
	v_max_f32_e32 v130, v59, v59
	v_max_f32_e32 v131, v58, v58
	v_max_f32_e32 v130, v131, v130
	v_max_f32_e32 v131, v61, v61
	v_max_f32_e32 v132, v60, v60
	v_max_f32_e32 v131, v132, v131
	v_max3_f32 v0, v0, v130, v131
	v_max_f32_e32 v130, v63, v63
	v_max_f32_e32 v131, v62, v62
	v_max_f32_e32 v130, v131, v130
	v_max_f32_e32 v131, v65, v65
	v_max_f32_e32 v132, v64, v64
	v_max_f32_e32 v131, v132, v131
	v_max3_f32 v0, v0, v130, v131
	ds_bpermute_b32 v130, v152, v0
	s_andn2_b64 vcc, exec, s[8:9]
	s_waitcnt lgkmcnt(0)
	v_max_f32_e32 v130, v130, v130
	v_max_f32_e32 v0, v0, v130
	v_max_f32_e32 v130, 0, v0
	s_cbranch_vccnz .LBB0_619
	v_exp_f32_e64 v132, -v130
	s_nop 0
	v_pk_mul_f32 v[32:33], v[32:33], v[132:133] op_sel_hi:[1,0]
	v_pk_mul_f32 v[30:31], v[30:31], v[132:133] op_sel_hi:[1,0]
	v_pk_mul_f32 v[28:29], v[28:29], v[132:133] op_sel_hi:[1,0]
	v_pk_mul_f32 v[26:27], v[26:27], v[132:133] op_sel_hi:[1,0]
	v_pk_mul_f32 v[24:25], v[24:25], v[132:133] op_sel_hi:[1,0]
	v_pk_mul_f32 v[22:23], v[22:23], v[132:133] op_sel_hi:[1,0]
	v_pk_mul_f32 v[20:21], v[20:21], v[132:133] op_sel_hi:[1,0]
	v_pk_mul_f32 v[18:19], v[18:19], v[132:133] op_sel_hi:[1,0]
	v_pk_mul_f32 v[16:17], v[16:17], v[132:133] op_sel_hi:[1,0]
	v_pk_mul_f32 v[14:15], v[14:15], v[132:133] op_sel_hi:[1,0]
	v_pk_mul_f32 v[12:13], v[12:13], v[132:133] op_sel_hi:[1,0]
	v_pk_mul_f32 v[10:11], v[10:11], v[132:133] op_sel_hi:[1,0]
	v_pk_mul_f32 v[8:9], v[8:9], v[132:133] op_sel_hi:[1,0]
	v_pk_mul_f32 v[6:7], v[6:7], v[132:133] op_sel_hi:[1,0]
	v_pk_mul_f32 v[4:5], v[4:5], v[132:133] op_sel_hi:[1,0]
	v_pk_mul_f32 v[2:3], v[2:3], v[132:133] op_sel_hi:[1,0]
	v_mul_f32_e32 v147, v147, v132

.LBB0_626:
	s_add_i32 s0, s7, s89
	s_add_i32 s8, s0, -3
	s_cmp_ge_i32 s8, s91
	v_readlane_b32 s9, v253, 10
	s_cselect_b64 s[0:1], -1, 0
	s_cmp_lt_i32 s8, s9
	s_cselect_b64 s[8:9], -1, 0
	s_and_b64 s[66:67], s[0:1], s[8:9]
	v_readlane_b32 s0, v253, 6
	s_add_i32 s8, s0, s88
	s_and_b64 s[0:1], s[66:67], exec
	s_cselect_b32 s0, s8, 0
	v_lshl_add_u32 v50, s0, 2, v150
	v_readlane_b32 s0, v253, 24
	v_readlane_b32 s1, v253, 25
	s_and_b64 vcc, s[66:67], s[0:1]
	v_mov_b32_e32 v0, 0
	v_lshl_add_u32 v51, v151, 2, v50
	v_mov_b32_e32 v50, 0
	s_mov_b64 s[96:97], 0x2000
	s_and_b64 vcc, exec, s[66:67]
	s_cbranch_vccz .Lnmo_out
	v_sub_u32_e32 v72, 0, v150
	v_sub_u32_e64 v72, v72, 32 clamp
	v_min_u32_e32 v72, 0xc0, v72
	v_lshlrev_b32_e32 v73, 2, v151
	v_sub_u32_e32 v72, v73, v72
	ds_read_b32 v52, v51 offset:32828
	ds_read_b32 v53, v51 offset:32832
	ds_read_b32 v54, v51 offset:32836
	ds_read_b32 v55, v51 offset:32840
	ds_read_b32 v56, v51 offset:32844
	ds_read_b32 v57, v51 offset:32848
	ds_read_b32 v58, v51 offset:32852
	ds_read_b32 v59, v51 offset:32856
	ds_read_b32 v60, v51 offset:32892
	ds_read_b32 v61, v51 offset:32896
	ds_read_b32 v62, v51 offset:32900
	ds_read_b32 v63, v51 offset:32904
	ds_read_b32 v64, v51 offset:32908
	ds_read_b32 v65, v51 offset:32912
	ds_read_b32 v66, v51 offset:32916
	ds_read_b32 v67, v51 offset:32920
	s_waitcnt lgkmcnt(8)
	v_add_u32_e32 v68, 0, v72
	v_add_u32_e32 v69, 4, v72
	v_add_u32_e32 v70, 8, v72
	v_add_u32_e32 v71, 12, v72
	v_fmac_f32_e32 v98, 0x3fb8aa3b, v52
	v_fmac_f32_e32 v99, 0x3fb8aa3b, v53
	v_fmac_f32_e32 v100, 0x3fb8aa3b, v54
	v_fmac_f32_e32 v101, 0x3fb8aa3b, v55
	v_cmp_gt_u32_e32 vcc, 64, v68
	v_cmp_gt_u32_e64 s[0:1], 64, v69
	v_cmp_gt_u32_e64 s[8:9], 64, v70
	v_cmp_gt_u32_e64 s[10:11], 64, v71
	v_cndmask_b32_e32 v98, v205, v98, vcc
	v_cndmask_b32_e64 v99, v205, v99, s[0:1]
	v_cndmask_b32_e64 v100, v205, v100, s[8:9]
	v_cndmask_b32_e64 v101, v205, v101, s[10:11]
	v_add_u32_e32 v68, 16, v72
	v_add_u32_e32 v69, 20, v72
	v_add_u32_e32 v70, 24, v72
	v_add_u32_e32 v71, 28, v72
	v_fmac_f32_e32 v102, 0x3fb8aa3b, v56
	v_fmac_f32_e32 v103, 0x3fb8aa3b, v57
	v_fmac_f32_e32 v104, 0x3fb8aa3b, v58
	v_fmac_f32_e32 v105, 0x3fb8aa3b, v59
	v_cmp_gt_u32_e32 vcc, 64, v68
	v_cmp_gt_u32_e64 s[0:1], 64, v69
	v_cmp_gt_u32_e64 s[8:9], 64, v70
	v_cmp_gt_u32_e64 s[10:11], 64, v71
	v_cndmask_b32_e32 v102, v205, v102, vcc
	v_cndmask_b32_e64 v103, v205, v103, s[0:1]
	v_cndmask_b32_e64 v104, v205, v104, s[8:9]
	v_cndmask_b32_e64 v105, v205, v105, s[10:11]
	ds_read_b32 v52, v51 offset:32956
	ds_read_b32 v53, v51 offset:32960
	ds_read_b32 v54, v51 offset:32964
	ds_read_b32 v55, v51 offset:32968
	ds_read_b32 v56, v51 offset:32972
	ds_read_b32 v57, v51 offset:32976
	ds_read_b32 v58, v51 offset:32980
	ds_read_b32 v59, v51 offset:32984
	s_waitcnt lgkmcnt(8)
	v_add_u32_e32 v68, 64, v72
	v_add_u32_e32 v69, 68, v72
	v_add_u32_e32 v70, 72, v72
	v_add_u32_e32 v71, 76, v72
	v_fmac_f32_e32 v106, 0x3fb8aa3b, v60
	v_fmac_f32_e32 v107, 0x3fb8aa3b, v61
	v_fmac_f32_e32 v108, 0x3fb8aa3b, v62
	v_fmac_f32_e32 v109, 0x3fb8aa3b, v63
	v_cmp_gt_u32_e32 vcc, 64, v68
	v_cmp_gt_u32_e64 s[0:1], 64, v69
	v_cmp_gt_u32_e64 s[8:9], 64, v70
	v_cmp_gt_u32_e64 s[10:11], 64, v71
	v_cndmask_b32_e32 v106, v205, v106, vcc
	v_cndmask_b32_e64 v107, v205, v107, s[0:1]
	v_cndmask_b32_e64 v108, v205, v108, s[8:9]
	v_cndmask_b32_e64 v109, v205, v109, s[10:11]
	v_add_u32_e32 v68, 80, v72
	v_add_u32_e32 v69, 84, v72
	v_add_u32_e32 v70, 88, v72
	v_add_u32_e32 v71, 92, v72
	v_fmac_f32_e32 v110, 0x3fb8aa3b, v64
	v_fmac_f32_e32 v111, 0x3fb8aa3b, v65
	v_fmac_f32_e32 v112, 0x3fb8aa3b, v66
	v_fmac_f32_e32 v113, 0x3fb8aa3b, v67
	v_cmp_gt_u32_e32 vcc, 64, v68
	v_cmp_gt_u32_e64 s[0:1], 64, v69
	v_cmp_gt_u32_e64 s[8:9], 64, v70
	v_cmp_gt_u32_e64 s[10:11], 64, v71
	v_cndmask_b32_e32 v110, v205, v110, vcc
	v_cndmask_b32_e64 v111, v205, v111, s[0:1]
	v_cndmask_b32_e64 v112, v205, v112, s[8:9]
	v_cndmask_b32_e64 v113, v205, v113, s[10:11]
	ds_read_b32 v60, v51 offset:33020
	ds_read_b32 v61, v51 offset:33024
	ds_read_b32 v62, v51 offset:33028
	ds_read_b32 v63, v51 offset:33032
	ds_read_b32 v64, v51 offset:33036
	ds_read_b32 v65, v51 offset:33040
	ds_read_b32 v66, v51 offset:33044
	ds_read_b32 v67, v51 offset:33048
	s_waitcnt lgkmcnt(8)
	v_add_u32_e32 v68, 128, v72
	v_add_u32_e32 v69, 132, v72
	v_add_u32_e32 v70, 136, v72
	v_add_u32_e32 v71, 140, v72
	v_fmac_f32_e32 v82, 0x3fb8aa3b, v52
	v_fmac_f32_e32 v83, 0x3fb8aa3b, v53
	v_fmac_f32_e32 v84, 0x3fb8aa3b, v54
	v_fmac_f32_e32 v85, 0x3fb8aa3b, v55
	v_cmp_gt_u32_e32 vcc, 64, v68
	v_cmp_gt_u32_e64 s[0:1], 64, v69
	v_cmp_gt_u32_e64 s[8:9], 64, v70
	v_cmp_gt_u32_e64 s[10:11], 64, v71
	v_cndmask_b32_e32 v82, v205, v82, vcc
	v_cndmask_b32_e64 v83, v205, v83, s[0:1]
	v_cndmask_b32_e64 v84, v205, v84, s[8:9]
	v_cndmask_b32_e64 v85, v205, v85, s[10:11]
	v_add_u32_e32 v68, 144, v72
	v_add_u32_e32 v69, 148, v72
	v_add_u32_e32 v70, 152, v72
	v_add_u32_e32 v71, 156, v72
	v_fmac_f32_e32 v86, 0x3fb8aa3b, v56
	v_fmac_f32_e32 v87, 0x3fb8aa3b, v57
	v_fmac_f32_e32 v88, 0x3fb8aa3b, v58
	v_fmac_f32_e32 v89, 0x3fb8aa3b, v59
	v_cmp_gt_u32_e32 vcc, 64, v68
	v_cmp_gt_u32_e64 s[0:1], 64, v69
	v_cmp_gt_u32_e64 s[8:9], 64, v70
	v_cmp_gt_u32_e64 s[10:11], 64, v71
	v_cndmask_b32_e32 v86, v205, v86, vcc
	v_cndmask_b32_e64 v87, v205, v87, s[0:1]
	v_cndmask_b32_e64 v88, v205, v88, s[8:9]
	v_cndmask_b32_e64 v89, v205, v89, s[10:11]
	s_waitcnt lgkmcnt(0)
	v_add_u32_e32 v68, 192, v72
	v_add_u32_e32 v69, 196, v72
	v_add_u32_e32 v70, 200, v72
	v_add_u32_e32 v71, 204, v72
	v_fmac_f32_e32 v90, 0x3fb8aa3b, v60
	v_fmac_f32_e32 v91, 0x3fb8aa3b, v61
	v_fmac_f32_e32 v92, 0x3fb8aa3b, v62
	v_fmac_f32_e32 v93, 0x3fb8aa3b, v63
	v_cmp_gt_u32_e32 vcc, 64, v68
	v_cmp_gt_u32_e64 s[0:1], 64, v69
	v_cmp_gt_u32_e64 s[8:9], 64, v70
	v_cmp_gt_u32_e64 s[10:11], 64, v71
	v_cndmask_b32_e32 v90, v205, v90, vcc
	v_cndmask_b32_e64 v91, v205, v91, s[0:1]
	v_cndmask_b32_e64 v92, v205, v92, s[8:9]
	v_cndmask_b32_e64 v93, v205, v93, s[10:11]
	v_add_u32_e32 v68, 208, v72
	v_add_u32_e32 v69, 212, v72
	v_add_u32_e32 v70, 216, v72
	v_add_u32_e32 v71, 220, v72
	v_fmac_f32_e32 v94, 0x3fb8aa3b, v64
	v_fmac_f32_e32 v95, 0x3fb8aa3b, v65
	v_fmac_f32_e32 v96, 0x3fb8aa3b, v66
	v_fmac_f32_e32 v97, 0x3fb8aa3b, v67
	v_cmp_gt_u32_e32 vcc, 64, v68
	v_cmp_gt_u32_e64 s[0:1], 64, v69
	v_cmp_gt_u32_e64 s[8:9], 64, v70
	v_cmp_gt_u32_e64 s[10:11], 64, v71
	v_cndmask_b32_e32 v94, v205, v94, vcc
	v_cndmask_b32_e64 v95, v205, v95, s[0:1]
	v_cndmask_b32_e64 v96, v205, v96, s[8:9]
	v_cndmask_b32_e64 v97, v205, v97, s[10:11]
	s_branch .Lnmo_done
; template <int DQK, int DV, int NAT, int VSHIFT, int COMB> ...
;     ...
;         for (int kt = 0; kt < nkt; kt += 2) {
;             ATT_STEP(sA0, sA1, sB0, sB1, kt, 0);
;             if (kt + 1 < nkt) ATT_STEP(sB0, sB1, sA0, sA1, kt + 1, 1);
;         }
.Lnmo_out:
	v_mov_b32_e32 v98, v205
	v_mov_b32_e32 v99, v205
	v_mov_b32_e32 v100, v205
	v_mov_b32_e32 v101, v205
	v_mov_b32_e32 v102, v205
	v_mov_b32_e32 v103, v205
	v_mov_b32_e32 v104, v205
	v_mov_b32_e32 v105, v205
	v_mov_b32_e32 v106, v205
	v_mov_b32_e32 v107, v205
	v_mov_b32_e32 v108, v205
	v_mov_b32_e32 v109, v205
	v_mov_b32_e32 v110, v205
	v_mov_b32_e32 v111, v205
	v_mov_b32_e32 v112, v205
	v_mov_b32_e32 v113, v205
	v_mov_b32_e32 v82, v205
	v_mov_b32_e32 v83, v205
	v_mov_b32_e32 v84, v205
	v_mov_b32_e32 v85, v205
	v_mov_b32_e32 v86, v205
	v_mov_b32_e32 v87, v205
	v_mov_b32_e32 v88, v205
	v_mov_b32_e32 v89, v205
	v_mov_b32_e32 v90, v205
	v_mov_b32_e32 v91, v205
	v_mov_b32_e32 v92, v205
	v_mov_b32_e32 v93, v205
	v_mov_b32_e32 v94, v205
	v_mov_b32_e32 v95, v205
	v_mov_b32_e32 v96, v205
	v_mov_b32_e32 v97, v205
.Lnmo_done:
	s_branch .LBB0_694
.LBB0_691:
	s_andn2_b64 vcc, exec, s[94:95]
	s_cbranch_vccnz .LBB0_625
